# phase 1 modulate loop: 12 loads per row issued together with one wait
# speedup vs baseline: 1.0021x; 1.0021x over previous
; __device__ __forceinline__ unsigned cvt_pk_bf16(float lo, float hi) { unsigned r; asm("v_cvt_pk_bf16_f32 %0, %1, %2" : "=v"(r) : "v"(lo), "v"(hi)); return r; }
; __global__ void __launch_bounds__(512, 2) mk_fwd(Args args) {
;     ...
;             for (int row = gw; row < MT; row += NGW) {
;                 const bool lat = row < ML;
;                 const float* xr = lat ? args.in[IN_X] + (size_t)row * DM : args.in[IN_CTX] + (size_t)(row - ML) * DM;
;                 const float* mp = MODS + (size_t)(lat ? (row >> 11) : 16) * 6144;
; #pragma unroll
;                 for (int j = 0; j < 4; ++j) { const int col = 4 * lane + 256 * j;
;                     const f32x4 v = *(const f32x4*)(xr + col), sh = *(const f32x4*)(mp + col), sc = *(const f32x4*)(mp + 1024 + col);
;                     const f32x4 hv = v * (sc + 1.0f) + sh;
;                     u32x2 w; w.x = cvt_pk_bf16(hv[0], hv[1]); w.y = cvt_pk_bf16(hv[2], hv[3]);
;                     *(u32x2*)(HO + (size_t)row * DM + col) = w; }
.LBB0_507:
	s_min_i32 s2, s0, 0x8000
	s_ashr_i32 s2, s2, 11
	s_mul_hi_i32 s3, s2, 0x6000
	s_mulk_i32 s2, 0x6000
	s_add_u32 s2, s12, s2
	s_addc_u32 s3, s13, s3
	s_add_u32 s8, s2, 0x1000
	s_addc_u32 s9, s3, 0
	v_lshl_add_u64 v[28:29], s[8:9], 0, v[0:1]
	v_lshl_add_u64 v[22:23], s[2:3], 0, v[0:1]
	global_load_dwordx4 v[30:33], v[28:29], off
	global_load_dwordx4 v[46:49], v0, s[6:7]
	global_load_dwordx4 v[62:65], v[22:23], off
	global_load_dwordx4 v[34:37], v[28:29], off offset:1024
	global_load_dwordx4 v[50:53], v0, s[6:7] offset:1024
	global_load_dwordx4 v[66:69], v[22:23], off offset:1024
	global_load_dwordx4 v[38:41], v[28:29], off offset:2048
	global_load_dwordx4 v[54:57], v0, s[6:7] offset:2048
	global_load_dwordx4 v[70:73], v[22:23], off offset:2048
	global_load_dwordx4 v[42:45], v[28:29], off offset:3072
	global_load_dwordx4 v[58:61], v0, s[6:7] offset:3072
	global_load_dwordx4 v[74:77], v[22:23], off offset:3072
	s_lshl_b64 s[2:3], s[38:39], 11
	v_lshl_add_u64 v[24:25], v[2:3], 0, s[2:3]
	s_add_u32 s0, s0, s24
	s_addc_u32 s1, s1, s25
	s_add_u32 s4, s4, s10
	s_addc_u32 s5, s5, s11
	s_cmp_gt_i32 s0, 0x8fff
	s_waitcnt vmcnt(0)
	v_pk_add_f32 v[30:31], v[30:31], 1.0 op_sel_hi:[1,0]
	v_pk_add_f32 v[32:33], v[32:33], 1.0 op_sel_hi:[1,0]
	v_pk_fma_f32 v[30:31], v[46:47], v[30:31], v[62:63]
	v_pk_fma_f32 v[32:33], v[48:49], v[32:33], v[64:65]
	v_cvt_pk_bf16_f32 v30, v30, v31
	v_cvt_pk_bf16_f32 v31, v32, v33
	flat_store_dwordx2 v[24:25], v[30:31]
	v_pk_add_f32 v[34:35], v[34:35], 1.0 op_sel_hi:[1,0]
	v_pk_add_f32 v[36:37], v[36:37], 1.0 op_sel_hi:[1,0]
	v_pk_fma_f32 v[34:35], v[50:51], v[34:35], v[66:67]
	v_pk_fma_f32 v[36:37], v[52:53], v[36:37], v[68:69]
	v_cvt_pk_bf16_f32 v34, v34, v35
	v_cvt_pk_bf16_f32 v35, v36, v37
	flat_store_dwordx2 v[24:25], v[34:35] offset:512
	v_pk_add_f32 v[38:39], v[38:39], 1.0 op_sel_hi:[1,0]
	v_pk_add_f32 v[40:41], v[40:41], 1.0 op_sel_hi:[1,0]
	v_pk_fma_f32 v[38:39], v[54:55], v[38:39], v[70:71]
	v_pk_fma_f32 v[40:41], v[56:57], v[40:41], v[72:73]
	v_cvt_pk_bf16_f32 v38, v38, v39
	v_cvt_pk_bf16_f32 v39, v40, v41
	flat_store_dwordx2 v[24:25], v[38:39] offset:1024
	v_pk_add_f32 v[42:43], v[42:43], 1.0 op_sel_hi:[1,0]
	v_pk_add_f32 v[44:45], v[44:45], 1.0 op_sel_hi:[1,0]
	v_pk_fma_f32 v[42:43], v[58:59], v[42:43], v[74:75]
	v_pk_fma_f32 v[44:45], v[60:61], v[44:45], v[76:77]
	v_cvt_pk_bf16_f32 v42, v42, v43
	v_cvt_pk_bf16_f32 v43, v44, v45
	flat_store_dwordx2 v[24:25], v[42:43] offset:1536
	v_mov_b32_e32 v5, v1
	v_mov_b32_e32 v7, v1
	v_mov_b32_e32 v9, v1
	s_cbranch_scc1 .LBB0_511
